# plus_ff1_lean_epilogue
# speedup vs baseline: 1.0066x; 1.0007x over previous
; DEVI unsigned pk_bf16(float lo, float hi) { unsigned r; asm("v_cvt_pk_bf16_f32 %0, %1, %2" : "=v"(r) : "v"(lo), "v"(hi)); return r; }
;     __device__ __forceinline__ void operator()(const f32x4 (&acc)[2][2][4][2], const Unit& u, int wr, int wc, int fr, int fq) const {
;         const int row0 = u.pm * BM + wr * 64 + fr, col0 = u.pn * BM + wc * 32 + 8 * fq;
; #pragma unroll
;         for (int ai = 0; ai < 2; ++ai)
; #pragma unroll
;             for (int m = 0; m < 4; ++m) { const int row = row0 + ai * HALF + m * 16;
; #pragma unroll
;                 for (int bj = 0; bj < 2; ++bj) { const int col = col0 + bj * HALF; f32x4 v0 = acc[ai][bj][m][0], v1 = acc[ai][bj][m][1];
;                     if (ACT == 1) {
; #pragma unroll
;                         for (int j = 0; j < 4; ++j) { const float a = fmaxf(v0[j], 0.f), b = fmaxf(v1[j], 0.f); v0[j] = a * a; v1[j] = b * b; } }
;                     if (col < gate0) { u32x4 w; w.x = pk_bf16(v0[0], v0[1]); w.y = pk_bf16(v0[2], v0[3]); w.z = pk_bf16(v1[0], v1[1]); w.w = pk_bf16(v1[2], v1[3]); *(u32x4*)(O + (size_t)row * ldo + col) = w; }
;                     else if (col < gate0 + 8) { float* gp = gates + (size_t)row * 8; *(f32x4*)gp = v0; *(f32x4*)(gp + 4) = v1; } } }
.LBB0_2180:
	v_lshl_add_u32 v164, s4, 8, v131
	v_lshl_or_b32 v162, s0, 8, v172
	v_mov_b32_e32 v165, 0
	v_mov_b32_e32 v163, 0
	s_mov_b32 s18, 0x20000
	s_mov_b32 s19, 0
	s_mov_b32 s20, 0xa0000
	s_mov_b32 s21, 0
	v_lshlrev_b64 v[166:167], 13, v[164:165]
	v_lshl_add_u64 v[166:167], s[60:61], 0, v[166:167]
	v_lshl_add_u64 v[166:167], v[162:163], 1, v[166:167]
	v_max_f32_e32 v120, 0, v120
	v_max_f32_e32 v121, 0, v121
	v_max_f32_e32 v122, 0, v122
	v_max_f32_e32 v123, 0, v123
	v_max_f32_e32 v124, 0, v124
	v_max_f32_e32 v125, 0, v125
	v_max_f32_e32 v126, 0, v126
	v_max_f32_e32 v127, 0, v127
	v_mul_f32_e32 v120, v120, v120
	v_mul_f32_e32 v121, v121, v121
	v_mul_f32_e32 v122, v122, v122
	v_mul_f32_e32 v123, v123, v123
	v_mul_f32_e32 v124, v124, v124
	v_mul_f32_e32 v125, v125, v125
	v_mul_f32_e32 v126, v126, v126
	v_mul_f32_e32 v127, v127, v127
	v_cvt_pk_bf16_f32 v120, v120, v121
	v_cvt_pk_bf16_f32 v121, v122, v123
	v_cvt_pk_bf16_f32 v122, v124, v125
	v_cvt_pk_bf16_f32 v123, v126, v127
	global_store_dwordx4 v[166:167], v[120:123], off
	v_max_f32_e32 v112, 0, v112
	v_max_f32_e32 v113, 0, v113
	v_max_f32_e32 v114, 0, v114
	v_max_f32_e32 v115, 0, v115
	v_max_f32_e32 v116, 0, v116
	v_max_f32_e32 v117, 0, v117
	v_max_f32_e32 v118, 0, v118
	v_max_f32_e32 v119, 0, v119
	v_mul_f32_e32 v112, v112, v112
	v_mul_f32_e32 v113, v113, v113
	v_mul_f32_e32 v114, v114, v114
	v_mul_f32_e32 v115, v115, v115
	v_mul_f32_e32 v116, v116, v116
	v_mul_f32_e32 v117, v117, v117
	v_mul_f32_e32 v118, v118, v118
	v_mul_f32_e32 v119, v119, v119
	v_cvt_pk_bf16_f32 v112, v112, v113
	v_cvt_pk_bf16_f32 v113, v114, v115
	v_cvt_pk_bf16_f32 v114, v116, v117
	v_cvt_pk_bf16_f32 v115, v118, v119
	global_store_dwordx4 v[166:167], v[112:115], off offset:256
	v_lshl_add_u64 v[166:167], s[18:19], 0, v[166:167]
	v_max_f32_e32 v104, 0, v104
	v_max_f32_e32 v105, 0, v105
	v_max_f32_e32 v106, 0, v106
	v_max_f32_e32 v107, 0, v107
	v_max_f32_e32 v108, 0, v108
	v_max_f32_e32 v109, 0, v109
	v_max_f32_e32 v110, 0, v110
	v_max_f32_e32 v111, 0, v111
	v_mul_f32_e32 v104, v104, v104
	v_mul_f32_e32 v105, v105, v105
	v_mul_f32_e32 v106, v106, v106
	v_mul_f32_e32 v107, v107, v107
	v_mul_f32_e32 v108, v108, v108
	v_mul_f32_e32 v109, v109, v109
	v_mul_f32_e32 v110, v110, v110
	v_mul_f32_e32 v111, v111, v111
	v_cvt_pk_bf16_f32 v104, v104, v105
	v_cvt_pk_bf16_f32 v105, v106, v107
	v_cvt_pk_bf16_f32 v106, v108, v109
	v_cvt_pk_bf16_f32 v107, v110, v111
	global_store_dwordx4 v[166:167], v[104:107], off
	v_max_f32_e32 v96, 0, v96
	v_max_f32_e32 v97, 0, v97
	v_max_f32_e32 v98, 0, v98
	v_max_f32_e32 v99, 0, v99
	v_max_f32_e32 v100, 0, v100
	v_max_f32_e32 v101, 0, v101
	v_max_f32_e32 v102, 0, v102
	v_max_f32_e32 v103, 0, v103
	v_mul_f32_e32 v96, v96, v96
	v_mul_f32_e32 v97, v97, v97
	v_mul_f32_e32 v98, v98, v98
	v_mul_f32_e32 v99, v99, v99
	v_mul_f32_e32 v100, v100, v100
	v_mul_f32_e32 v101, v101, v101
	v_mul_f32_e32 v102, v102, v102
	v_mul_f32_e32 v103, v103, v103
	v_cvt_pk_bf16_f32 v96, v96, v97
	v_cvt_pk_bf16_f32 v97, v98, v99
	v_cvt_pk_bf16_f32 v98, v100, v101
	v_cvt_pk_bf16_f32 v99, v102, v103
	global_store_dwordx4 v[166:167], v[96:99], off offset:256
	v_lshl_add_u64 v[166:167], s[18:19], 0, v[166:167]
	v_max_f32_e32 v88, 0, v88
	v_max_f32_e32 v89, 0, v89
	v_max_f32_e32 v90, 0, v90
	v_max_f32_e32 v91, 0, v91
	v_max_f32_e32 v92, 0, v92
	v_max_f32_e32 v93, 0, v93
	v_max_f32_e32 v94, 0, v94
	v_max_f32_e32 v95, 0, v95
	v_mul_f32_e32 v88, v88, v88
	v_mul_f32_e32 v89, v89, v89
	v_mul_f32_e32 v90, v90, v90
	v_mul_f32_e32 v91, v91, v91
	v_mul_f32_e32 v92, v92, v92
	v_mul_f32_e32 v93, v93, v93
	v_mul_f32_e32 v94, v94, v94
	v_mul_f32_e32 v95, v95, v95
	v_cvt_pk_bf16_f32 v88, v88, v89
	v_cvt_pk_bf16_f32 v89, v90, v91
	v_cvt_pk_bf16_f32 v90, v92, v93
	v_cvt_pk_bf16_f32 v91, v94, v95
	global_store_dwordx4 v[166:167], v[88:91], off
	v_max_f32_e32 v80, 0, v80
	v_max_f32_e32 v81, 0, v81
	v_max_f32_e32 v82, 0, v82
	v_max_f32_e32 v83, 0, v83
	v_max_f32_e32 v84, 0, v84
	v_max_f32_e32 v85, 0, v85
	v_max_f32_e32 v86, 0, v86
	v_max_f32_e32 v87, 0, v87
	v_mul_f32_e32 v80, v80, v80
	v_mul_f32_e32 v81, v81, v81
	v_mul_f32_e32 v82, v82, v82
	v_mul_f32_e32 v83, v83, v83
	v_mul_f32_e32 v84, v84, v84
	v_mul_f32_e32 v85, v85, v85
	v_mul_f32_e32 v86, v86, v86
	v_mul_f32_e32 v87, v87, v87
	v_cvt_pk_bf16_f32 v80, v80, v81
	v_cvt_pk_bf16_f32 v81, v82, v83
	v_cvt_pk_bf16_f32 v82, v84, v85
	v_cvt_pk_bf16_f32 v83, v86, v87
	global_store_dwordx4 v[166:167], v[80:83], off offset:256
	v_lshl_add_u64 v[166:167], s[18:19], 0, v[166:167]
	v_max_f32_e32 v72, 0, v72
	v_max_f32_e32 v73, 0, v73
	v_max_f32_e32 v74, 0, v74
	v_max_f32_e32 v75, 0, v75
	v_max_f32_e32 v76, 0, v76
	v_max_f32_e32 v77, 0, v77
	v_max_f32_e32 v78, 0, v78
	v_max_f32_e32 v79, 0, v79
	v_mul_f32_e32 v72, v72, v72
	v_mul_f32_e32 v73, v73, v73
	v_mul_f32_e32 v74, v74, v74
	v_mul_f32_e32 v75, v75, v75
	v_mul_f32_e32 v76, v76, v76
	v_mul_f32_e32 v77, v77, v77
	v_mul_f32_e32 v78, v78, v78
	v_mul_f32_e32 v79, v79, v79
	v_cvt_pk_bf16_f32 v72, v72, v73
	v_cvt_pk_bf16_f32 v73, v74, v75
	v_cvt_pk_bf16_f32 v74, v76, v77
	v_cvt_pk_bf16_f32 v75, v78, v79
	global_store_dwordx4 v[166:167], v[72:75], off
	v_max_f32_e32 v64, 0, v64
	v_max_f32_e32 v65, 0, v65
	v_max_f32_e32 v66, 0, v66
	v_max_f32_e32 v67, 0, v67
	v_max_f32_e32 v68, 0, v68
	v_max_f32_e32 v69, 0, v69
	v_max_f32_e32 v70, 0, v70
	v_max_f32_e32 v71, 0, v71
	v_mul_f32_e32 v64, v64, v64
	v_mul_f32_e32 v65, v65, v65
	v_mul_f32_e32 v66, v66, v66
	v_mul_f32_e32 v67, v67, v67
	v_mul_f32_e32 v68, v68, v68
	v_mul_f32_e32 v69, v69, v69
; DEVI unsigned pk_bf16(float lo, float hi) { unsigned r; asm("v_cvt_pk_bf16_f32 %0, %1, %2" : "=v"(r) : "v"(lo), "v"(hi)); return r; }
;     __device__ __forceinline__ void operator()(const f32x4 (&acc)[2][2][4][2], const Unit& u, int wr, int wc, int fr, int fq) const {
;         const int row0 = u.pm * BM + wr * 64 + fr, col0 = u.pn * BM + wc * 32 + 8 * fq;
; #pragma unroll
;         for (int ai = 0; ai < 2; ++ai)
; #pragma unroll
;             for (int m = 0; m < 4; ++m) { const int row = row0 + ai * HALF + m * 16;
; #pragma unroll
;                 for (int bj = 0; bj < 2; ++bj) { const int col = col0 + bj * HALF; f32x4 v0 = acc[ai][bj][m][0], v1 = acc[ai][bj][m][1];
;                     if (ACT == 1) {
; #pragma unroll
;                         for (int j = 0; j < 4; ++j) { const float a = fmaxf(v0[j], 0.f), b = fmaxf(v1[j], 0.f); v0[j] = a * a; v1[j] = b * b; } }
;                     if (col < gate0) { u32x4 w; w.x = pk_bf16(v0[0], v0[1]); w.y = pk_bf16(v0[2], v0[3]); w.z = pk_bf16(v1[0], v1[1]); w.w = pk_bf16(v1[2], v1[3]); *(u32x4*)(O + (size_t)row * ldo + col) = w; }
;                     else if (col < gate0 + 8) { float* gp = gates + (size_t)row * 8; *(f32x4*)gp = v0; *(f32x4*)(gp + 4) = v1; } } }
	v_mul_f32_e32 v70, v70, v70
	v_mul_f32_e32 v71, v71, v71
	v_cvt_pk_bf16_f32 v64, v64, v65
	v_cvt_pk_bf16_f32 v65, v66, v67
	v_cvt_pk_bf16_f32 v66, v68, v69
	v_cvt_pk_bf16_f32 v67, v70, v71
	global_store_dwordx4 v[166:167], v[64:67], off offset:256
	v_lshl_add_u64 v[166:167], s[20:21], 0, v[166:167]
	v_max_f32_e32 v56, 0, v56
	v_max_f32_e32 v57, 0, v57
	v_max_f32_e32 v58, 0, v58
	v_max_f32_e32 v59, 0, v59
	v_max_f32_e32 v60, 0, v60
	v_max_f32_e32 v61, 0, v61
	v_max_f32_e32 v62, 0, v62
	v_max_f32_e32 v63, 0, v63
	v_mul_f32_e32 v56, v56, v56
	v_mul_f32_e32 v57, v57, v57
	v_mul_f32_e32 v58, v58, v58
	v_mul_f32_e32 v59, v59, v59
	v_mul_f32_e32 v60, v60, v60
	v_mul_f32_e32 v61, v61, v61
	v_mul_f32_e32 v62, v62, v62
	v_mul_f32_e32 v63, v63, v63
	v_cvt_pk_bf16_f32 v56, v56, v57
	v_cvt_pk_bf16_f32 v57, v58, v59
	v_cvt_pk_bf16_f32 v58, v60, v61
	v_cvt_pk_bf16_f32 v59, v62, v63
	global_store_dwordx4 v[166:167], v[56:59], off
	v_max_f32_e32 v48, 0, v48
	v_max_f32_e32 v49, 0, v49
	v_max_f32_e32 v50, 0, v50
	v_max_f32_e32 v51, 0, v51
	v_max_f32_e32 v52, 0, v52
	v_max_f32_e32 v53, 0, v53
	v_max_f32_e32 v54, 0, v54
	v_max_f32_e32 v55, 0, v55
	v_mul_f32_e32 v48, v48, v48
	v_mul_f32_e32 v49, v49, v49
	v_mul_f32_e32 v50, v50, v50
	v_mul_f32_e32 v51, v51, v51
	v_mul_f32_e32 v52, v52, v52
	v_mul_f32_e32 v53, v53, v53
	v_mul_f32_e32 v54, v54, v54
	v_mul_f32_e32 v55, v55, v55
	v_cvt_pk_bf16_f32 v48, v48, v49
	v_cvt_pk_bf16_f32 v49, v50, v51
	v_cvt_pk_bf16_f32 v50, v52, v53
	v_cvt_pk_bf16_f32 v51, v54, v55
	global_store_dwordx4 v[166:167], v[48:51], off offset:256
	v_lshl_add_u64 v[166:167], s[18:19], 0, v[166:167]
	v_max_f32_e32 v40, 0, v40
	v_max_f32_e32 v41, 0, v41
	v_max_f32_e32 v42, 0, v42
	v_max_f32_e32 v43, 0, v43
	v_max_f32_e32 v44, 0, v44
	v_max_f32_e32 v45, 0, v45
	v_max_f32_e32 v46, 0, v46
	v_max_f32_e32 v47, 0, v47
	v_mul_f32_e32 v40, v40, v40
	v_mul_f32_e32 v41, v41, v41
	v_mul_f32_e32 v42, v42, v42
	v_mul_f32_e32 v43, v43, v43
	v_mul_f32_e32 v44, v44, v44
	v_mul_f32_e32 v45, v45, v45
	v_mul_f32_e32 v46, v46, v46
	v_mul_f32_e32 v47, v47, v47
	v_cvt_pk_bf16_f32 v40, v40, v41
	v_cvt_pk_bf16_f32 v41, v42, v43
	v_cvt_pk_bf16_f32 v42, v44, v45
	v_cvt_pk_bf16_f32 v43, v46, v47
	global_store_dwordx4 v[166:167], v[40:43], off
	v_max_f32_e32 v32, 0, v32
	v_max_f32_e32 v33, 0, v33
	v_max_f32_e32 v34, 0, v34
	v_max_f32_e32 v35, 0, v35
	v_max_f32_e32 v36, 0, v36
	v_max_f32_e32 v37, 0, v37
	v_max_f32_e32 v38, 0, v38
	v_max_f32_e32 v39, 0, v39
	v_mul_f32_e32 v32, v32, v32
	v_mul_f32_e32 v33, v33, v33
	v_mul_f32_e32 v34, v34, v34
	v_mul_f32_e32 v35, v35, v35
	v_mul_f32_e32 v36, v36, v36
	v_mul_f32_e32 v37, v37, v37
	v_mul_f32_e32 v38, v38, v38
	v_mul_f32_e32 v39, v39, v39
	v_cvt_pk_bf16_f32 v32, v32, v33
	v_cvt_pk_bf16_f32 v33, v34, v35
	v_cvt_pk_bf16_f32 v34, v36, v37
	v_cvt_pk_bf16_f32 v35, v38, v39
	global_store_dwordx4 v[166:167], v[32:35], off offset:256
	v_lshl_add_u64 v[166:167], s[18:19], 0, v[166:167]
	v_max_f32_e32 v24, 0, v24
	v_max_f32_e32 v25, 0, v25
	v_max_f32_e32 v26, 0, v26
	v_max_f32_e32 v27, 0, v27
	v_max_f32_e32 v28, 0, v28
	v_max_f32_e32 v29, 0, v29
	v_max_f32_e32 v30, 0, v30
	v_max_f32_e32 v31, 0, v31
	v_mul_f32_e32 v24, v24, v24
	v_mul_f32_e32 v25, v25, v25
	v_mul_f32_e32 v26, v26, v26
	v_mul_f32_e32 v27, v27, v27
	v_mul_f32_e32 v28, v28, v28
	v_mul_f32_e32 v29, v29, v29
	v_mul_f32_e32 v30, v30, v30
	v_mul_f32_e32 v31, v31, v31
	v_cvt_pk_bf16_f32 v24, v24, v25
	v_cvt_pk_bf16_f32 v25, v26, v27
	v_cvt_pk_bf16_f32 v26, v28, v29
	v_cvt_pk_bf16_f32 v27, v30, v31
	global_store_dwordx4 v[166:167], v[24:27], off
	v_max_f32_e32 v16, 0, v16
	v_max_f32_e32 v17, 0, v17
	v_max_f32_e32 v18, 0, v18
	v_max_f32_e32 v19, 0, v19
	v_max_f32_e32 v20, 0, v20
	v_max_f32_e32 v21, 0, v21
	v_max_f32_e32 v22, 0, v22
	v_max_f32_e32 v23, 0, v23
	v_mul_f32_e32 v16, v16, v16
	v_mul_f32_e32 v17, v17, v17
	v_mul_f32_e32 v18, v18, v18
	v_mul_f32_e32 v19, v19, v19
	v_mul_f32_e32 v20, v20, v20
	v_mul_f32_e32 v21, v21, v21
	v_mul_f32_e32 v22, v22, v22
	v_mul_f32_e32 v23, v23, v23
	v_cvt_pk_bf16_f32 v16, v16, v17
	v_cvt_pk_bf16_f32 v17, v18, v19
	v_cvt_pk_bf16_f32 v18, v20, v21
	v_cvt_pk_bf16_f32 v19, v22, v23
	global_store_dwordx4 v[166:167], v[16:19], off offset:256
	v_lshl_add_u64 v[166:167], s[18:19], 0, v[166:167]
	v_max_f32_e32 v8, 0, v8
	v_max_f32_e32 v9, 0, v9
	v_max_f32_e32 v10, 0, v10
	v_max_f32_e32 v11, 0, v11
	v_max_f32_e32 v12, 0, v12
	v_max_f32_e32 v13, 0, v13
	v_max_f32_e32 v14, 0, v14
	v_max_f32_e32 v15, 0, v15
	v_mul_f32_e32 v8, v8, v8
	v_mul_f32_e32 v9, v9, v9
	v_mul_f32_e32 v10, v10, v10
	v_mul_f32_e32 v11, v11, v11
	v_mul_f32_e32 v12, v12, v12
	v_mul_f32_e32 v13, v13, v13
	v_mul_f32_e32 v14, v14, v14
	v_mul_f32_e32 v15, v15, v15
	v_cvt_pk_bf16_f32 v8, v8, v9
	v_cvt_pk_bf16_f32 v9, v10, v11
	v_cvt_pk_bf16_f32 v10, v12, v13
	v_cvt_pk_bf16_f32 v11, v14, v15
	global_store_dwordx4 v[166:167], v[8:11], off
	v_max_f32_e32 v0, 0, v0
	v_max_f32_e32 v1, 0, v1
	v_max_f32_e32 v2, 0, v2
	v_max_f32_e32 v3, 0, v3
	v_max_f32_e32 v4, 0, v4
	v_max_f32_e32 v5, 0, v5
	v_max_f32_e32 v6, 0, v6
	v_max_f32_e32 v7, 0, v7
	v_mul_f32_e32 v0, v0, v0
	v_mul_f32_e32 v1, v1, v1
	v_mul_f32_e32 v2, v2, v2
	v_mul_f32_e32 v3, v3, v3
	v_mul_f32_e32 v4, v4, v4
	v_mul_f32_e32 v5, v5, v5
	v_mul_f32_e32 v6, v6, v6
	v_mul_f32_e32 v7, v7, v7
	v_cvt_pk_bf16_f32 v0, v0, v1
	v_cvt_pk_bf16_f32 v1, v2, v3
	v_cvt_pk_bf16_f32 v2, v4, v5
	v_cvt_pk_bf16_f32 v3, v6, v7
	global_store_dwordx4 v[166:167], v[0:3], off offset:256
	s_andn2_b64 vcc, exec, s[2:3]
	s_mov_b64 s[0:1], -1
	s_cbranch_vccnz .LBB0_2173
